# conv_phase inner loop hand-written: 24 loads per 8-token step issued up front with counted waits
# baseline (speedup 1.0000x reference)
; __device__ __forceinline__ float bflo(unsigned u) { return __uint_as_float(u << 16); }
; __device__ __forceinline__ float bfhi(unsigned u) { return __uint_as_float(u & 0xffff0000u); }
; __device__ __forceinline__ unsigned pk2(float lo, float hi) { return pg8::cvt_pk_bf16(lo, hi); }
; __device__ __forceinline__ void conv_phase(const bf16* proj, const float* cw  , bf16* Y, int gtid, int GT) {
;     ...
;         for (int i = 0; i < 16; ++i) {
;             const size_t ro = (size_t)(t0 + i) * NIN + c0;
;             const u32x4 xv = __builtin_nontemporal_load((const u32x4*)(proj + ro + C_XV)), gc = __builtin_nontemporal_load((const u32x4*)(proj + ro + C_GC)), gb = __builtin_nontemporal_load((const u32x4*)(proj + ro + C_GB));
;             float u0[8], y[8];
; #pragma unroll
;             for (int j = 0; j < 4; ++j) { u0[2 * j] = bflo(xv[j]) * bflo(gc[j]); u0[2 * j + 1] = bfhi(xv[j]) * bfhi(gc[j]); }
; #pragma unroll
;             for (int j = 0; j < 8; ++j) y[j] = w0[j] * um2[j] + w1[j] * um1[j] + w2[j] * u0[j];
;             u32x4 o;
; #pragma unroll
;             for (int j = 0; j < 4; ++j) o[j] = pk2(y[2 * j] * bflo(gb[j]), y[2 * j + 1] * bfhi(gb[j]));
;             *(u32x4*)(Y + (size_t)(t0 + i) * D + c0) = o;
; #pragma unroll
;             for (int j = 0; j < 8; ++j) { um2[j] = um1[j]; um1[j] = u0[j]; }
;         }
.LBB0_486:
	v_lshl_add_u64 v[28:29], v[34:35], 0, v[136:137]
	s_mov_b64 s[4:5], 0xe601000
	v_lshl_add_u64 v[28:29], v[28:29], 0, s[4:5]
	s_mov_b64 s[4:5], 0x3200
	global_load_dwordx4 v[198:201], v[28:29], off offset:-4096 nt
	global_load_dwordx4 v[202:205], v[28:29], off nt
	global_load_dwordx4 v[206:209], v[28:29], off offset:-2048 nt
	v_lshl_add_u64 v[28:29], v[28:29], 0, s[4:5]
	global_load_dwordx4 v[210:213], v[28:29], off offset:-4096 nt
	global_load_dwordx4 v[214:217], v[28:29], off nt
	global_load_dwordx4 v[218:221], v[28:29], off offset:-2048 nt
	v_lshl_add_u64 v[28:29], v[28:29], 0, s[4:5]
	global_load_dwordx4 v[222:225], v[28:29], off offset:-4096 nt
	global_load_dwordx4 v[226:229], v[28:29], off nt
	global_load_dwordx4 v[230:233], v[28:29], off offset:-2048 nt
	v_lshl_add_u64 v[28:29], v[28:29], 0, s[4:5]
	global_load_dwordx4 v[234:237], v[28:29], off offset:-4096 nt
	global_load_dwordx4 v[238:241], v[28:29], off nt
	global_load_dwordx4 v[242:245], v[28:29], off offset:-2048 nt
	v_lshl_add_u64 v[28:29], v[28:29], 0, s[4:5]
	global_load_dwordx4 v[100:103], v[28:29], off offset:-4096 nt
	global_load_dwordx4 v[104:107], v[28:29], off nt
	global_load_dwordx4 v[108:111], v[28:29], off offset:-2048 nt
	v_lshl_add_u64 v[28:29], v[28:29], 0, s[4:5]
	global_load_dwordx4 v[112:115], v[28:29], off offset:-4096 nt
	global_load_dwordx4 v[116:119], v[28:29], off nt
	global_load_dwordx4 v[120:123], v[28:29], off offset:-2048 nt
	v_lshl_add_u64 v[28:29], v[28:29], 0, s[4:5]
	global_load_dwordx4 v[124:127], v[28:29], off offset:-4096 nt
	global_load_dwordx4 v[128:131], v[28:29], off nt
	global_load_dwordx4 v[150:153], v[28:29], off offset:-2048 nt
	v_lshl_add_u64 v[28:29], v[28:29], 0, s[4:5]
	global_load_dwordx4 v[154:157], v[28:29], off offset:-4096 nt
	global_load_dwordx4 v[158:161], v[28:29], off nt
	global_load_dwordx4 v[162:165], v[28:29], off offset:-2048 nt
	v_lshl_add_u64 v[30:31], v[32:33], 0, v[136:137]
	s_mov_b64 s[4:5], 0x1ae00000
	v_lshl_add_u64 v[30:31], v[30:31], 0, s[4:5]
	s_mov_b64 s[4:5], 0x1000
	s_add_i32 s2, s2, -8
	s_waitcnt vmcnt(21)
	v_lshlrev_b32_e32 v60, 16, v198
	v_and_b32_e32 v61, 0xffff0000, v198
	v_lshlrev_b32_e32 v76, 16, v202
	v_and_b32_e32 v77, 0xffff0000, v202
	v_lshlrev_b32_e32 v62, 16, v199
	v_and_b32_e32 v63, 0xffff0000, v199
	v_lshlrev_b32_e32 v78, 16, v203
	v_and_b32_e32 v79, 0xffff0000, v203
	v_lshlrev_b32_e32 v64, 16, v200
	v_and_b32_e32 v65, 0xffff0000, v200
	v_lshlrev_b32_e32 v80, 16, v204
	v_and_b32_e32 v81, 0xffff0000, v204
	v_lshlrev_b32_e32 v66, 16, v201
	v_and_b32_e32 v67, 0xffff0000, v201
	v_lshlrev_b32_e32 v82, 16, v205
	v_and_b32_e32 v83, 0xffff0000, v205
	v_pk_mul_f32 v[60:61], v[60:61], v[76:77]
	v_pk_mul_f32 v[62:63], v[62:63], v[78:79]
	v_pk_mul_f32 v[64:65], v[64:65], v[80:81]
	v_pk_mul_f32 v[66:67], v[66:67], v[82:83]
	v_pk_mul_f32 v[44:45], v[12:13], v[42:43]
	v_mov_b32_e32 v43, v42
	v_add_f32_e32 v68, v44, v45
	v_mov_b32_e32 v42, v60
	v_fmac_f32_e32 v68, v20, v60
	v_pk_mul_f32 v[44:45], v[8:9], v[54:55]
	v_mov_b32_e32 v55, v54
	v_add_f32_e32 v69, v44, v45
	v_mov_b32_e32 v54, v61
	v_fmac_f32_e32 v69, v21, v61
	v_pk_mul_f32 v[44:45], v[14:15], v[40:41]
	v_mov_b32_e32 v41, v40
	v_add_f32_e32 v70, v44, v45
	v_mov_b32_e32 v40, v62
	v_fmac_f32_e32 v70, v22, v62
	v_pk_mul_f32 v[44:45], v[10:11], v[52:53]
	v_mov_b32_e32 v53, v52
	v_add_f32_e32 v71, v44, v45
	v_mov_b32_e32 v52, v63
	v_fmac_f32_e32 v71, v23, v63
	v_pk_mul_f32 v[44:45], v[16:17], v[38:39]
	v_mov_b32_e32 v39, v38
	v_add_f32_e32 v72, v44, v45
	v_mov_b32_e32 v38, v64
	v_fmac_f32_e32 v72, v24, v64
	v_pk_mul_f32 v[44:45], v[4:5], v[50:51]
	v_mov_b32_e32 v51, v50
	v_add_f32_e32 v73, v44, v45
	v_mov_b32_e32 v50, v65
	v_fmac_f32_e32 v73, v25, v65
	v_pk_mul_f32 v[44:45], v[18:19], v[36:37]
	v_mov_b32_e32 v37, v36
	v_add_f32_e32 v46, v44, v45
	v_mov_b32_e32 v36, v66
	v_fmac_f32_e32 v46, v26, v66
	v_pk_mul_f32 v[44:45], v[6:7], v[48:49]
	v_mov_b32_e32 v49, v48
	v_add_f32_e32 v47, v44, v45
	v_mov_b32_e32 v48, v67
	v_fmac_f32_e32 v47, v27, v67
	v_lshlrev_b32_e32 v76, 16, v206
	v_and_b32_e32 v77, 0xffff0000, v206
	v_lshlrev_b32_e32 v78, 16, v207
	v_and_b32_e32 v79, 0xffff0000, v207
	v_lshlrev_b32_e32 v80, 16, v208
	v_and_b32_e32 v81, 0xffff0000, v208
	v_lshlrev_b32_e32 v82, 16, v209
	v_and_b32_e32 v83, 0xffff0000, v209
	v_mul_f32_e32 v68, v68, v76
	v_mul_f32_e32 v69, v69, v77
	v_mul_f32_e32 v70, v70, v78
	v_mul_f32_e32 v71, v71, v79
	v_mul_f32_e32 v72, v72, v80
	v_mul_f32_e32 v73, v73, v81
	v_mul_f32_e32 v46, v46, v82
	v_mul_f32_e32 v47, v47, v83
	v_cvt_pk_bf16_f32 v56, v68, v69
	v_cvt_pk_bf16_f32 v57, v70, v71
	v_cvt_pk_bf16_f32 v58, v72, v73
	v_cvt_pk_bf16_f32 v59, v46, v47
	global_store_dwordx4 v[30:31], v[56:59], off
	v_lshl_add_u64 v[30:31], v[30:31], 0, s[4:5]
	s_waitcnt vmcnt(19)
; __device__ __forceinline__ float bflo(unsigned u) { return __uint_as_float(u << 16); }
; __device__ __forceinline__ float bfhi(unsigned u) { return __uint_as_float(u & 0xffff0000u); }
; __device__ __forceinline__ unsigned pk2(float lo, float hi) { return pg8::cvt_pk_bf16(lo, hi); }
; __device__ __forceinline__ void conv_phase(const bf16* proj, const float* cw  , bf16* Y, int gtid, int GT) {
;     ...
;             const u32x4 xv = __builtin_nontemporal_load((const u32x4*)(proj + ro + C_XV)), gc = __builtin_nontemporal_load((const u32x4*)(proj + ro + C_GC)), gb = __builtin_nontemporal_load((const u32x4*)(proj + ro + C_GB));
;             float u0[8], y[8];
; #pragma unroll
;             for (int j = 0; j < 4; ++j) { u0[2 * j] = bflo(xv[j]) * bflo(gc[j]); u0[2 * j + 1] = bfhi(xv[j]) * bfhi(gc[j]); }
; #pragma unroll
;             for (int j = 0; j < 8; ++j) y[j] = w0[j] * um2[j] + w1[j] * um1[j] + w2[j] * u0[j];
;             u32x4 o;
; #pragma unroll
;             for (int j = 0; j < 4; ++j) o[j] = pk2(y[2 * j] * bflo(gb[j]), y[2 * j + 1] * bfhi(gb[j]));
;             *(u32x4*)(Y + (size_t)(t0 + i) * D + c0) = o;
; #pragma unroll
;             for (int j = 0; j < 8; ++j) { um2[j] = um1[j]; um1[j] = u0[j]; }
	v_lshlrev_b32_e32 v60, 16, v210
	v_and_b32_e32 v61, 0xffff0000, v210
	v_lshlrev_b32_e32 v76, 16, v214
	v_and_b32_e32 v77, 0xffff0000, v214
	v_lshlrev_b32_e32 v62, 16, v211
	v_and_b32_e32 v63, 0xffff0000, v211
	v_lshlrev_b32_e32 v78, 16, v215
	v_and_b32_e32 v79, 0xffff0000, v215
	v_lshlrev_b32_e32 v64, 16, v212
	v_and_b32_e32 v65, 0xffff0000, v212
	v_lshlrev_b32_e32 v80, 16, v216
	v_and_b32_e32 v81, 0xffff0000, v216
	v_lshlrev_b32_e32 v66, 16, v213
	v_and_b32_e32 v67, 0xffff0000, v213
	v_lshlrev_b32_e32 v82, 16, v217
	v_and_b32_e32 v83, 0xffff0000, v217
	v_pk_mul_f32 v[60:61], v[60:61], v[76:77]
	v_pk_mul_f32 v[62:63], v[62:63], v[78:79]
	v_pk_mul_f32 v[64:65], v[64:65], v[80:81]
	v_pk_mul_f32 v[66:67], v[66:67], v[82:83]
	v_pk_mul_f32 v[44:45], v[12:13], v[42:43]
	v_mov_b32_e32 v43, v42
	v_add_f32_e32 v68, v44, v45
	v_mov_b32_e32 v42, v60
	v_fmac_f32_e32 v68, v20, v60
	v_pk_mul_f32 v[44:45], v[8:9], v[54:55]
	v_mov_b32_e32 v55, v54
	v_add_f32_e32 v69, v44, v45
	v_mov_b32_e32 v54, v61
	v_fmac_f32_e32 v69, v21, v61
	v_pk_mul_f32 v[44:45], v[14:15], v[40:41]
	v_mov_b32_e32 v41, v40
	v_add_f32_e32 v70, v44, v45
	v_mov_b32_e32 v40, v62
	v_fmac_f32_e32 v70, v22, v62
	v_pk_mul_f32 v[44:45], v[10:11], v[52:53]
	v_mov_b32_e32 v53, v52
	v_add_f32_e32 v71, v44, v45
	v_mov_b32_e32 v52, v63
	v_fmac_f32_e32 v71, v23, v63
	v_pk_mul_f32 v[44:45], v[16:17], v[38:39]
	v_mov_b32_e32 v39, v38
	v_add_f32_e32 v72, v44, v45
	v_mov_b32_e32 v38, v64
	v_fmac_f32_e32 v72, v24, v64
	v_pk_mul_f32 v[44:45], v[4:5], v[50:51]
	v_mov_b32_e32 v51, v50
	v_add_f32_e32 v73, v44, v45
	v_mov_b32_e32 v50, v65
	v_fmac_f32_e32 v73, v25, v65
	v_pk_mul_f32 v[44:45], v[18:19], v[36:37]
	v_mov_b32_e32 v37, v36
	v_add_f32_e32 v46, v44, v45
	v_mov_b32_e32 v36, v66
	v_fmac_f32_e32 v46, v26, v66
	v_pk_mul_f32 v[44:45], v[6:7], v[48:49]
	v_mov_b32_e32 v49, v48
	v_add_f32_e32 v47, v44, v45
	v_mov_b32_e32 v48, v67
	v_fmac_f32_e32 v47, v27, v67
	v_lshlrev_b32_e32 v76, 16, v218
	v_and_b32_e32 v77, 0xffff0000, v218
	v_lshlrev_b32_e32 v78, 16, v219
	v_and_b32_e32 v79, 0xffff0000, v219
	v_lshlrev_b32_e32 v80, 16, v220
	v_and_b32_e32 v81, 0xffff0000, v220
	v_lshlrev_b32_e32 v82, 16, v221
	v_and_b32_e32 v83, 0xffff0000, v221
	v_mul_f32_e32 v68, v68, v76
	v_mul_f32_e32 v69, v69, v77
	v_mul_f32_e32 v70, v70, v78
	v_mul_f32_e32 v71, v71, v79
	v_mul_f32_e32 v72, v72, v80
	v_mul_f32_e32 v73, v73, v81
	v_mul_f32_e32 v46, v46, v82
	v_mul_f32_e32 v47, v47, v83
	v_cvt_pk_bf16_f32 v56, v68, v69
	v_cvt_pk_bf16_f32 v57, v70, v71
	v_cvt_pk_bf16_f32 v58, v72, v73
	v_cvt_pk_bf16_f32 v59, v46, v47
	global_store_dwordx4 v[30:31], v[56:59], off
	v_lshl_add_u64 v[30:31], v[30:31], 0, s[4:5]
	s_waitcnt vmcnt(17)
	v_lshlrev_b32_e32 v60, 16, v222
	v_and_b32_e32 v61, 0xffff0000, v222
	v_lshlrev_b32_e32 v76, 16, v226
	v_and_b32_e32 v77, 0xffff0000, v226
	v_lshlrev_b32_e32 v62, 16, v223
	v_and_b32_e32 v63, 0xffff0000, v223
	v_lshlrev_b32_e32 v78, 16, v227
	v_and_b32_e32 v79, 0xffff0000, v227
	v_lshlrev_b32_e32 v64, 16, v224
	v_and_b32_e32 v65, 0xffff0000, v224
	v_lshlrev_b32_e32 v80, 16, v228
	v_and_b32_e32 v81, 0xffff0000, v228
	v_lshlrev_b32_e32 v66, 16, v225
	v_and_b32_e32 v67, 0xffff0000, v225
	v_lshlrev_b32_e32 v82, 16, v229
	v_and_b32_e32 v83, 0xffff0000, v229
	v_pk_mul_f32 v[60:61], v[60:61], v[76:77]
	v_pk_mul_f32 v[62:63], v[62:63], v[78:79]
	v_pk_mul_f32 v[64:65], v[64:65], v[80:81]
	v_pk_mul_f32 v[66:67], v[66:67], v[82:83]
	v_pk_mul_f32 v[44:45], v[12:13], v[42:43]
	v_mov_b32_e32 v43, v42
	v_add_f32_e32 v68, v44, v45
	v_mov_b32_e32 v42, v60
	v_fmac_f32_e32 v68, v20, v60
	v_pk_mul_f32 v[44:45], v[8:9], v[54:55]
	v_mov_b32_e32 v55, v54
	v_add_f32_e32 v69, v44, v45
	v_mov_b32_e32 v54, v61
	v_fmac_f32_e32 v69, v21, v61
	v_pk_mul_f32 v[44:45], v[14:15], v[40:41]
	v_mov_b32_e32 v41, v40
	v_add_f32_e32 v70, v44, v45
	v_mov_b32_e32 v40, v62
	v_fmac_f32_e32 v70, v22, v62
	v_pk_mul_f32 v[44:45], v[10:11], v[52:53]
	v_mov_b32_e32 v53, v52
	v_add_f32_e32 v71, v44, v45
	v_mov_b32_e32 v52, v63
	v_fmac_f32_e32 v71, v23, v63
	v_pk_mul_f32 v[44:45], v[16:17], v[38:39]
	v_mov_b32_e32 v39, v38
	v_add_f32_e32 v72, v44, v45
	v_mov_b32_e32 v38, v64
	v_fmac_f32_e32 v72, v24, v64
	v_pk_mul_f32 v[44:45], v[4:5], v[50:51]
	v_mov_b32_e32 v51, v50
	v_add_f32_e32 v73, v44, v45
	v_mov_b32_e32 v50, v65
	v_fmac_f32_e32 v73, v25, v65
	v_pk_mul_f32 v[44:45], v[18:19], v[36:37]
	v_mov_b32_e32 v37, v36
	v_add_f32_e32 v46, v44, v45
	v_mov_b32_e32 v36, v66
	v_fmac_f32_e32 v46, v26, v66
	v_pk_mul_f32 v[44:45], v[6:7], v[48:49]
	v_mov_b32_e32 v49, v48
	v_add_f32_e32 v47, v44, v45
	v_mov_b32_e32 v48, v67
	v_fmac_f32_e32 v47, v27, v67
	v_lshlrev_b32_e32 v76, 16, v230
	v_and_b32_e32 v77, 0xffff0000, v230
	v_lshlrev_b32_e32 v78, 16, v231
	v_and_b32_e32 v79, 0xffff0000, v231
	v_lshlrev_b32_e32 v80, 16, v232
	v_and_b32_e32 v81, 0xffff0000, v232
	v_lshlrev_b32_e32 v82, 16, v233
	v_and_b32_e32 v83, 0xffff0000, v233
	v_mul_f32_e32 v68, v68, v76
	v_mul_f32_e32 v69, v69, v77
	v_mul_f32_e32 v70, v70, v78
	v_mul_f32_e32 v71, v71, v79
	v_mul_f32_e32 v72, v72, v80
	v_mul_f32_e32 v73, v73, v81
	v_mul_f32_e32 v46, v46, v82
	v_mul_f32_e32 v47, v47, v83
	v_cvt_pk_bf16_f32 v56, v68, v69
	v_cvt_pk_bf16_f32 v57, v70, v71
	v_cvt_pk_bf16_f32 v58, v72, v73
	v_cvt_pk_bf16_f32 v59, v46, v47
	global_store_dwordx4 v[30:31], v[56:59], off
	v_lshl_add_u64 v[30:31], v[30:31], 0, s[4:5]
	s_waitcnt vmcnt(15)
; __device__ __forceinline__ float bflo(unsigned u) { return __uint_as_float(u << 16); }
; __device__ __forceinline__ float bfhi(unsigned u) { return __uint_as_float(u & 0xffff0000u); }
; __device__ __forceinline__ unsigned pk2(float lo, float hi) { return pg8::cvt_pk_bf16(lo, hi); }
; __device__ __forceinline__ void conv_phase(const bf16* proj, const float* cw  , bf16* Y, int gtid, int GT) {
;     ...
;             const u32x4 xv = __builtin_nontemporal_load((const u32x4*)(proj + ro + C_XV)), gc = __builtin_nontemporal_load((const u32x4*)(proj + ro + C_GC)), gb = __builtin_nontemporal_load((const u32x4*)(proj + ro + C_GB));
;             float u0[8], y[8];
; #pragma unroll
;             for (int j = 0; j < 4; ++j) { u0[2 * j] = bflo(xv[j]) * bflo(gc[j]); u0[2 * j + 1] = bfhi(xv[j]) * bfhi(gc[j]); }
; #pragma unroll
;             for (int j = 0; j < 8; ++j) y[j] = w0[j] * um2[j] + w1[j] * um1[j] + w2[j] * u0[j];
;             u32x4 o;
; #pragma unroll
;             for (int j = 0; j < 4; ++j) o[j] = pk2(y[2 * j] * bflo(gb[j]), y[2 * j + 1] * bfhi(gb[j]));
;             *(u32x4*)(Y + (size_t)(t0 + i) * D + c0) = o;
; #pragma unroll
;             for (int j = 0; j < 8; ++j) { um2[j] = um1[j]; um1[j] = u0[j]; }
	v_lshlrev_b32_e32 v60, 16, v234
	v_and_b32_e32 v61, 0xffff0000, v234
	v_lshlrev_b32_e32 v76, 16, v238
	v_and_b32_e32 v77, 0xffff0000, v238
	v_lshlrev_b32_e32 v62, 16, v235
	v_and_b32_e32 v63, 0xffff0000, v235
	v_lshlrev_b32_e32 v78, 16, v239
	v_and_b32_e32 v79, 0xffff0000, v239
	v_lshlrev_b32_e32 v64, 16, v236
	v_and_b32_e32 v65, 0xffff0000, v236
	v_lshlrev_b32_e32 v80, 16, v240
	v_and_b32_e32 v81, 0xffff0000, v240
	v_lshlrev_b32_e32 v66, 16, v237
	v_and_b32_e32 v67, 0xffff0000, v237
	v_lshlrev_b32_e32 v82, 16, v241
	v_and_b32_e32 v83, 0xffff0000, v241
	v_pk_mul_f32 v[60:61], v[60:61], v[76:77]
	v_pk_mul_f32 v[62:63], v[62:63], v[78:79]
	v_pk_mul_f32 v[64:65], v[64:65], v[80:81]
	v_pk_mul_f32 v[66:67], v[66:67], v[82:83]
	v_pk_mul_f32 v[44:45], v[12:13], v[42:43]
	v_mov_b32_e32 v43, v42
	v_add_f32_e32 v68, v44, v45
	v_mov_b32_e32 v42, v60
	v_fmac_f32_e32 v68, v20, v60
	v_pk_mul_f32 v[44:45], v[8:9], v[54:55]
	v_mov_b32_e32 v55, v54
	v_add_f32_e32 v69, v44, v45
	v_mov_b32_e32 v54, v61
	v_fmac_f32_e32 v69, v21, v61
	v_pk_mul_f32 v[44:45], v[14:15], v[40:41]
	v_mov_b32_e32 v41, v40
	v_add_f32_e32 v70, v44, v45
	v_mov_b32_e32 v40, v62
	v_fmac_f32_e32 v70, v22, v62
	v_pk_mul_f32 v[44:45], v[10:11], v[52:53]
	v_mov_b32_e32 v53, v52
	v_add_f32_e32 v71, v44, v45
	v_mov_b32_e32 v52, v63
	v_fmac_f32_e32 v71, v23, v63
	v_pk_mul_f32 v[44:45], v[16:17], v[38:39]
	v_mov_b32_e32 v39, v38
	v_add_f32_e32 v72, v44, v45
	v_mov_b32_e32 v38, v64
	v_fmac_f32_e32 v72, v24, v64
	v_pk_mul_f32 v[44:45], v[4:5], v[50:51]
	v_mov_b32_e32 v51, v50
	v_add_f32_e32 v73, v44, v45
	v_mov_b32_e32 v50, v65
	v_fmac_f32_e32 v73, v25, v65
	v_pk_mul_f32 v[44:45], v[18:19], v[36:37]
	v_mov_b32_e32 v37, v36
	v_add_f32_e32 v46, v44, v45
	v_mov_b32_e32 v36, v66
	v_fmac_f32_e32 v46, v26, v66
	v_pk_mul_f32 v[44:45], v[6:7], v[48:49]
	v_mov_b32_e32 v49, v48
	v_add_f32_e32 v47, v44, v45
	v_mov_b32_e32 v48, v67
	v_fmac_f32_e32 v47, v27, v67
	v_lshlrev_b32_e32 v76, 16, v242
	v_and_b32_e32 v77, 0xffff0000, v242
	v_lshlrev_b32_e32 v78, 16, v243
	v_and_b32_e32 v79, 0xffff0000, v243
	v_lshlrev_b32_e32 v80, 16, v244
	v_and_b32_e32 v81, 0xffff0000, v244
	v_lshlrev_b32_e32 v82, 16, v245
	v_and_b32_e32 v83, 0xffff0000, v245
	v_mul_f32_e32 v68, v68, v76
	v_mul_f32_e32 v69, v69, v77
	v_mul_f32_e32 v70, v70, v78
	v_mul_f32_e32 v71, v71, v79
	v_mul_f32_e32 v72, v72, v80
	v_mul_f32_e32 v73, v73, v81
	v_mul_f32_e32 v46, v46, v82
	v_mul_f32_e32 v47, v47, v83
	v_cvt_pk_bf16_f32 v56, v68, v69
	v_cvt_pk_bf16_f32 v57, v70, v71
	v_cvt_pk_bf16_f32 v58, v72, v73
	v_cvt_pk_bf16_f32 v59, v46, v47
	global_store_dwordx4 v[30:31], v[56:59], off
	v_lshl_add_u64 v[30:31], v[30:31], 0, s[4:5]
	s_waitcnt vmcnt(13)
	v_lshlrev_b32_e32 v60, 16, v100
	v_and_b32_e32 v61, 0xffff0000, v100
	v_lshlrev_b32_e32 v76, 16, v104
	v_and_b32_e32 v77, 0xffff0000, v104
	v_lshlrev_b32_e32 v62, 16, v101
	v_and_b32_e32 v63, 0xffff0000, v101
	v_lshlrev_b32_e32 v78, 16, v105
	v_and_b32_e32 v79, 0xffff0000, v105
	v_lshlrev_b32_e32 v64, 16, v102
	v_and_b32_e32 v65, 0xffff0000, v102
	v_lshlrev_b32_e32 v80, 16, v106
	v_and_b32_e32 v81, 0xffff0000, v106
	v_lshlrev_b32_e32 v66, 16, v103
	v_and_b32_e32 v67, 0xffff0000, v103
	v_lshlrev_b32_e32 v82, 16, v107
	v_and_b32_e32 v83, 0xffff0000, v107
	v_pk_mul_f32 v[60:61], v[60:61], v[76:77]
	v_pk_mul_f32 v[62:63], v[62:63], v[78:79]
	v_pk_mul_f32 v[64:65], v[64:65], v[80:81]
	v_pk_mul_f32 v[66:67], v[66:67], v[82:83]
	v_pk_mul_f32 v[44:45], v[12:13], v[42:43]
	v_mov_b32_e32 v43, v42
	v_add_f32_e32 v68, v44, v45
	v_mov_b32_e32 v42, v60
	v_fmac_f32_e32 v68, v20, v60
	v_pk_mul_f32 v[44:45], v[8:9], v[54:55]
	v_mov_b32_e32 v55, v54
	v_add_f32_e32 v69, v44, v45
	v_mov_b32_e32 v54, v61
	v_fmac_f32_e32 v69, v21, v61
	v_pk_mul_f32 v[44:45], v[14:15], v[40:41]
	v_mov_b32_e32 v41, v40
	v_add_f32_e32 v70, v44, v45
	v_mov_b32_e32 v40, v62
	v_fmac_f32_e32 v70, v22, v62
	v_pk_mul_f32 v[44:45], v[10:11], v[52:53]
	v_mov_b32_e32 v53, v52
	v_add_f32_e32 v71, v44, v45
	v_mov_b32_e32 v52, v63
	v_fmac_f32_e32 v71, v23, v63
	v_pk_mul_f32 v[44:45], v[16:17], v[38:39]
	v_mov_b32_e32 v39, v38
	v_add_f32_e32 v72, v44, v45
	v_mov_b32_e32 v38, v64
	v_fmac_f32_e32 v72, v24, v64
	v_pk_mul_f32 v[44:45], v[4:5], v[50:51]
	v_mov_b32_e32 v51, v50
	v_add_f32_e32 v73, v44, v45
	v_mov_b32_e32 v50, v65
	v_fmac_f32_e32 v73, v25, v65
	v_pk_mul_f32 v[44:45], v[18:19], v[36:37]
	v_mov_b32_e32 v37, v36
	v_add_f32_e32 v46, v44, v45
	v_mov_b32_e32 v36, v66
	v_fmac_f32_e32 v46, v26, v66
	v_pk_mul_f32 v[44:45], v[6:7], v[48:49]
	v_mov_b32_e32 v49, v48
	v_add_f32_e32 v47, v44, v45
	v_mov_b32_e32 v48, v67
	v_fmac_f32_e32 v47, v27, v67
	v_lshlrev_b32_e32 v76, 16, v108
	v_and_b32_e32 v77, 0xffff0000, v108
	v_lshlrev_b32_e32 v78, 16, v109
	v_and_b32_e32 v79, 0xffff0000, v109
	v_lshlrev_b32_e32 v80, 16, v110
	v_and_b32_e32 v81, 0xffff0000, v110
	v_lshlrev_b32_e32 v82, 16, v111
	v_and_b32_e32 v83, 0xffff0000, v111
	v_mul_f32_e32 v68, v68, v76
	v_mul_f32_e32 v69, v69, v77
	v_mul_f32_e32 v70, v70, v78
	v_mul_f32_e32 v71, v71, v79
	v_mul_f32_e32 v72, v72, v80
	v_mul_f32_e32 v73, v73, v81
	v_mul_f32_e32 v46, v46, v82
	v_mul_f32_e32 v47, v47, v83
	v_cvt_pk_bf16_f32 v56, v68, v69
	v_cvt_pk_bf16_f32 v57, v70, v71
	v_cvt_pk_bf16_f32 v58, v72, v73
	v_cvt_pk_bf16_f32 v59, v46, v47
	global_store_dwordx4 v[30:31], v[56:59], off
	v_lshl_add_u64 v[30:31], v[30:31], 0, s[4:5]
	s_waitcnt vmcnt(11)
; __device__ __forceinline__ float bflo(unsigned u) { return __uint_as_float(u << 16); }
; __device__ __forceinline__ float bfhi(unsigned u) { return __uint_as_float(u & 0xffff0000u); }
; __device__ __forceinline__ unsigned pk2(float lo, float hi) { return pg8::cvt_pk_bf16(lo, hi); }
; __device__ __forceinline__ void conv_phase(const bf16* proj, const float* cw  , bf16* Y, int gtid, int GT) {
;     ...
;             const u32x4 xv = __builtin_nontemporal_load((const u32x4*)(proj + ro + C_XV)), gc = __builtin_nontemporal_load((const u32x4*)(proj + ro + C_GC)), gb = __builtin_nontemporal_load((const u32x4*)(proj + ro + C_GB));
;             float u0[8], y[8];
; #pragma unroll
;             for (int j = 0; j < 4; ++j) { u0[2 * j] = bflo(xv[j]) * bflo(gc[j]); u0[2 * j + 1] = bfhi(xv[j]) * bfhi(gc[j]); }
; #pragma unroll
;             for (int j = 0; j < 8; ++j) y[j] = w0[j] * um2[j] + w1[j] * um1[j] + w2[j] * u0[j];
;             u32x4 o;
; #pragma unroll
;             for (int j = 0; j < 4; ++j) o[j] = pk2(y[2 * j] * bflo(gb[j]), y[2 * j + 1] * bfhi(gb[j]));
;             *(u32x4*)(Y + (size_t)(t0 + i) * D + c0) = o;
; #pragma unroll
;             for (int j = 0; j < 8; ++j) { um2[j] = um1[j]; um1[j] = u0[j]; }
	v_lshlrev_b32_e32 v60, 16, v112
	v_and_b32_e32 v61, 0xffff0000, v112
	v_lshlrev_b32_e32 v76, 16, v116
	v_and_b32_e32 v77, 0xffff0000, v116
	v_lshlrev_b32_e32 v62, 16, v113
	v_and_b32_e32 v63, 0xffff0000, v113
	v_lshlrev_b32_e32 v78, 16, v117
	v_and_b32_e32 v79, 0xffff0000, v117
	v_lshlrev_b32_e32 v64, 16, v114
	v_and_b32_e32 v65, 0xffff0000, v114
	v_lshlrev_b32_e32 v80, 16, v118
	v_and_b32_e32 v81, 0xffff0000, v118
	v_lshlrev_b32_e32 v66, 16, v115
	v_and_b32_e32 v67, 0xffff0000, v115
	v_lshlrev_b32_e32 v82, 16, v119
	v_and_b32_e32 v83, 0xffff0000, v119
	v_pk_mul_f32 v[60:61], v[60:61], v[76:77]
	v_pk_mul_f32 v[62:63], v[62:63], v[78:79]
	v_pk_mul_f32 v[64:65], v[64:65], v[80:81]
	v_pk_mul_f32 v[66:67], v[66:67], v[82:83]
	v_pk_mul_f32 v[44:45], v[12:13], v[42:43]
	v_mov_b32_e32 v43, v42
	v_add_f32_e32 v68, v44, v45
	v_mov_b32_e32 v42, v60
	v_fmac_f32_e32 v68, v20, v60
	v_pk_mul_f32 v[44:45], v[8:9], v[54:55]
	v_mov_b32_e32 v55, v54
	v_add_f32_e32 v69, v44, v45
	v_mov_b32_e32 v54, v61
	v_fmac_f32_e32 v69, v21, v61
	v_pk_mul_f32 v[44:45], v[14:15], v[40:41]
	v_mov_b32_e32 v41, v40
	v_add_f32_e32 v70, v44, v45
	v_mov_b32_e32 v40, v62
	v_fmac_f32_e32 v70, v22, v62
	v_pk_mul_f32 v[44:45], v[10:11], v[52:53]
	v_mov_b32_e32 v53, v52
	v_add_f32_e32 v71, v44, v45
	v_mov_b32_e32 v52, v63
	v_fmac_f32_e32 v71, v23, v63
	v_pk_mul_f32 v[44:45], v[16:17], v[38:39]
	v_mov_b32_e32 v39, v38
	v_add_f32_e32 v72, v44, v45
	v_mov_b32_e32 v38, v64
	v_fmac_f32_e32 v72, v24, v64
	v_pk_mul_f32 v[44:45], v[4:5], v[50:51]
	v_mov_b32_e32 v51, v50
	v_add_f32_e32 v73, v44, v45
	v_mov_b32_e32 v50, v65
	v_fmac_f32_e32 v73, v25, v65
	v_pk_mul_f32 v[44:45], v[18:19], v[36:37]
	v_mov_b32_e32 v37, v36
	v_add_f32_e32 v46, v44, v45
	v_mov_b32_e32 v36, v66
	v_fmac_f32_e32 v46, v26, v66
	v_pk_mul_f32 v[44:45], v[6:7], v[48:49]
	v_mov_b32_e32 v49, v48
	v_add_f32_e32 v47, v44, v45
	v_mov_b32_e32 v48, v67
	v_fmac_f32_e32 v47, v27, v67
	v_lshlrev_b32_e32 v76, 16, v120
	v_and_b32_e32 v77, 0xffff0000, v120
	v_lshlrev_b32_e32 v78, 16, v121
	v_and_b32_e32 v79, 0xffff0000, v121
	v_lshlrev_b32_e32 v80, 16, v122
	v_and_b32_e32 v81, 0xffff0000, v122
	v_lshlrev_b32_e32 v82, 16, v123
	v_and_b32_e32 v83, 0xffff0000, v123
	v_mul_f32_e32 v68, v68, v76
	v_mul_f32_e32 v69, v69, v77
	v_mul_f32_e32 v70, v70, v78
	v_mul_f32_e32 v71, v71, v79
	v_mul_f32_e32 v72, v72, v80
	v_mul_f32_e32 v73, v73, v81
	v_mul_f32_e32 v46, v46, v82
	v_mul_f32_e32 v47, v47, v83
	v_cvt_pk_bf16_f32 v56, v68, v69
	v_cvt_pk_bf16_f32 v57, v70, v71
	v_cvt_pk_bf16_f32 v58, v72, v73
	v_cvt_pk_bf16_f32 v59, v46, v47
	global_store_dwordx4 v[30:31], v[56:59], off
	v_lshl_add_u64 v[30:31], v[30:31], 0, s[4:5]
	s_waitcnt vmcnt(9)
	v_lshlrev_b32_e32 v60, 16, v124
	v_and_b32_e32 v61, 0xffff0000, v124
	v_lshlrev_b32_e32 v76, 16, v128
	v_and_b32_e32 v77, 0xffff0000, v128
	v_lshlrev_b32_e32 v62, 16, v125
	v_and_b32_e32 v63, 0xffff0000, v125
	v_lshlrev_b32_e32 v78, 16, v129
	v_and_b32_e32 v79, 0xffff0000, v129
	v_lshlrev_b32_e32 v64, 16, v126
	v_and_b32_e32 v65, 0xffff0000, v126
	v_lshlrev_b32_e32 v80, 16, v130
	v_and_b32_e32 v81, 0xffff0000, v130
	v_lshlrev_b32_e32 v66, 16, v127
	v_and_b32_e32 v67, 0xffff0000, v127
	v_lshlrev_b32_e32 v82, 16, v131
	v_and_b32_e32 v83, 0xffff0000, v131
	v_pk_mul_f32 v[60:61], v[60:61], v[76:77]
	v_pk_mul_f32 v[62:63], v[62:63], v[78:79]
	v_pk_mul_f32 v[64:65], v[64:65], v[80:81]
	v_pk_mul_f32 v[66:67], v[66:67], v[82:83]
	v_pk_mul_f32 v[44:45], v[12:13], v[42:43]
	v_mov_b32_e32 v43, v42
	v_add_f32_e32 v68, v44, v45
	v_mov_b32_e32 v42, v60
	v_fmac_f32_e32 v68, v20, v60
	v_pk_mul_f32 v[44:45], v[8:9], v[54:55]
	v_mov_b32_e32 v55, v54
	v_add_f32_e32 v69, v44, v45
	v_mov_b32_e32 v54, v61
	v_fmac_f32_e32 v69, v21, v61
	v_pk_mul_f32 v[44:45], v[14:15], v[40:41]
	v_mov_b32_e32 v41, v40
	v_add_f32_e32 v70, v44, v45
	v_mov_b32_e32 v40, v62
	v_fmac_f32_e32 v70, v22, v62
	v_pk_mul_f32 v[44:45], v[10:11], v[52:53]
	v_mov_b32_e32 v53, v52
	v_add_f32_e32 v71, v44, v45
	v_mov_b32_e32 v52, v63
	v_fmac_f32_e32 v71, v23, v63
	v_pk_mul_f32 v[44:45], v[16:17], v[38:39]
	v_mov_b32_e32 v39, v38
	v_add_f32_e32 v72, v44, v45
	v_mov_b32_e32 v38, v64
	v_fmac_f32_e32 v72, v24, v64
	v_pk_mul_f32 v[44:45], v[4:5], v[50:51]
	v_mov_b32_e32 v51, v50
	v_add_f32_e32 v73, v44, v45
	v_mov_b32_e32 v50, v65
	v_fmac_f32_e32 v73, v25, v65
	v_pk_mul_f32 v[44:45], v[18:19], v[36:37]
	v_mov_b32_e32 v37, v36
	v_add_f32_e32 v46, v44, v45
	v_mov_b32_e32 v36, v66
	v_fmac_f32_e32 v46, v26, v66
	v_pk_mul_f32 v[44:45], v[6:7], v[48:49]
	v_mov_b32_e32 v49, v48
	v_add_f32_e32 v47, v44, v45
	v_mov_b32_e32 v48, v67
	v_fmac_f32_e32 v47, v27, v67
	v_lshlrev_b32_e32 v76, 16, v150
	v_and_b32_e32 v77, 0xffff0000, v150
	v_lshlrev_b32_e32 v78, 16, v151
	v_and_b32_e32 v79, 0xffff0000, v151
	v_lshlrev_b32_e32 v80, 16, v152
	v_and_b32_e32 v81, 0xffff0000, v152
	v_lshlrev_b32_e32 v82, 16, v153
	v_and_b32_e32 v83, 0xffff0000, v153
	v_mul_f32_e32 v68, v68, v76
	v_mul_f32_e32 v69, v69, v77
	v_mul_f32_e32 v70, v70, v78
	v_mul_f32_e32 v71, v71, v79
	v_mul_f32_e32 v72, v72, v80
	v_mul_f32_e32 v73, v73, v81
	v_mul_f32_e32 v46, v46, v82
	v_mul_f32_e32 v47, v47, v83
	v_cvt_pk_bf16_f32 v56, v68, v69
	v_cvt_pk_bf16_f32 v57, v70, v71
	v_cvt_pk_bf16_f32 v58, v72, v73
	v_cvt_pk_bf16_f32 v59, v46, v47
	global_store_dwordx4 v[30:31], v[56:59], off
	v_lshl_add_u64 v[30:31], v[30:31], 0, s[4:5]
	s_waitcnt vmcnt(7)
; __device__ __forceinline__ float bflo(unsigned u) { return __uint_as_float(u << 16); }
; __device__ __forceinline__ float bfhi(unsigned u) { return __uint_as_float(u & 0xffff0000u); }
; __device__ __forceinline__ unsigned pk2(float lo, float hi) { return pg8::cvt_pk_bf16(lo, hi); }
; __device__ __forceinline__ void conv_phase(const bf16* proj, const float* cw  , bf16* Y, int gtid, int GT) {
;     for (int id = gtid; id < (T / 16) * (DCONV / 8); id += GT) {
;     ...
;             const u32x4 xv = __builtin_nontemporal_load((const u32x4*)(proj + ro + C_XV)), gc = __builtin_nontemporal_load((const u32x4*)(proj + ro + C_GC)), gb = __builtin_nontemporal_load((const u32x4*)(proj + ro + C_GB));
;             float u0[8], y[8];
; #pragma unroll
;             for (int j = 0; j < 4; ++j) { u0[2 * j] = bflo(xv[j]) * bflo(gc[j]); u0[2 * j + 1] = bfhi(xv[j]) * bfhi(gc[j]); }
; #pragma unroll
;             for (int j = 0; j < 8; ++j) y[j] = w0[j] * um2[j] + w1[j] * um1[j] + w2[j] * u0[j];
;             u32x4 o;
; #pragma unroll
;             for (int j = 0; j < 4; ++j) o[j] = pk2(y[2 * j] * bflo(gb[j]), y[2 * j + 1] * bfhi(gb[j]));
;             *(u32x4*)(Y + (size_t)(t0 + i) * D + c0) = o;
; #pragma unroll
;             for (int j = 0; j < 8; ++j) { um2[j] = um1[j]; um1[j] = u0[j]; }
;         }
	v_lshlrev_b32_e32 v60, 16, v154
	v_and_b32_e32 v61, 0xffff0000, v154
	v_lshlrev_b32_e32 v76, 16, v158
	v_and_b32_e32 v77, 0xffff0000, v158
	v_lshlrev_b32_e32 v62, 16, v155
	v_and_b32_e32 v63, 0xffff0000, v155
	v_lshlrev_b32_e32 v78, 16, v159
	v_and_b32_e32 v79, 0xffff0000, v159
	v_lshlrev_b32_e32 v64, 16, v156
	v_and_b32_e32 v65, 0xffff0000, v156
	v_lshlrev_b32_e32 v80, 16, v160
	v_and_b32_e32 v81, 0xffff0000, v160
	v_lshlrev_b32_e32 v66, 16, v157
	v_and_b32_e32 v67, 0xffff0000, v157
	v_lshlrev_b32_e32 v82, 16, v161
	v_and_b32_e32 v83, 0xffff0000, v161
	v_pk_mul_f32 v[60:61], v[60:61], v[76:77]
	v_pk_mul_f32 v[62:63], v[62:63], v[78:79]
	v_pk_mul_f32 v[64:65], v[64:65], v[80:81]
	v_pk_mul_f32 v[66:67], v[66:67], v[82:83]
	v_pk_mul_f32 v[44:45], v[12:13], v[42:43]
	v_mov_b32_e32 v43, v42
	v_add_f32_e32 v68, v44, v45
	v_mov_b32_e32 v42, v60
	v_fmac_f32_e32 v68, v20, v60
	v_pk_mul_f32 v[44:45], v[8:9], v[54:55]
	v_mov_b32_e32 v55, v54
	v_add_f32_e32 v69, v44, v45
	v_mov_b32_e32 v54, v61
	v_fmac_f32_e32 v69, v21, v61
	v_pk_mul_f32 v[44:45], v[14:15], v[40:41]
	v_mov_b32_e32 v41, v40
	v_add_f32_e32 v70, v44, v45
	v_mov_b32_e32 v40, v62
	v_fmac_f32_e32 v70, v22, v62
	v_pk_mul_f32 v[44:45], v[10:11], v[52:53]
	v_mov_b32_e32 v53, v52
	v_add_f32_e32 v71, v44, v45
	v_mov_b32_e32 v52, v63
	v_fmac_f32_e32 v71, v23, v63
	v_pk_mul_f32 v[44:45], v[16:17], v[38:39]
	v_mov_b32_e32 v39, v38
	v_add_f32_e32 v72, v44, v45
	v_mov_b32_e32 v38, v64
	v_fmac_f32_e32 v72, v24, v64
	v_pk_mul_f32 v[44:45], v[4:5], v[50:51]
	v_mov_b32_e32 v51, v50
	v_add_f32_e32 v73, v44, v45
	v_mov_b32_e32 v50, v65
	v_fmac_f32_e32 v73, v25, v65
	v_pk_mul_f32 v[44:45], v[18:19], v[36:37]
	v_mov_b32_e32 v37, v36
	v_add_f32_e32 v46, v44, v45
	v_mov_b32_e32 v36, v66
	v_fmac_f32_e32 v46, v26, v66
	v_pk_mul_f32 v[44:45], v[6:7], v[48:49]
	v_mov_b32_e32 v49, v48
	v_add_f32_e32 v47, v44, v45
	v_mov_b32_e32 v48, v67
	v_fmac_f32_e32 v47, v27, v67
	v_lshlrev_b32_e32 v76, 16, v162
	v_and_b32_e32 v77, 0xffff0000, v162
	v_lshlrev_b32_e32 v78, 16, v163
	v_and_b32_e32 v79, 0xffff0000, v163
	v_lshlrev_b32_e32 v80, 16, v164
	v_and_b32_e32 v81, 0xffff0000, v164
	v_lshlrev_b32_e32 v82, 16, v165
	v_and_b32_e32 v83, 0xffff0000, v165
	v_mul_f32_e32 v68, v68, v76
	v_mul_f32_e32 v69, v69, v77
	v_mul_f32_e32 v70, v70, v78
	v_mul_f32_e32 v71, v71, v79
	v_mul_f32_e32 v72, v72, v80
	v_mul_f32_e32 v73, v73, v81
	v_mul_f32_e32 v46, v46, v82
	v_mul_f32_e32 v47, v47, v83
	v_cvt_pk_bf16_f32 v56, v68, v69
	v_cvt_pk_bf16_f32 v57, v70, v71
	v_cvt_pk_bf16_f32 v58, v72, v73
	v_cvt_pk_bf16_f32 v59, v46, v47
	global_store_dwordx4 v[30:31], v[56:59], off
	s_mov_b64 s[4:5], 0x19000
	v_lshl_add_u64 v[34:35], v[34:35], 0, s[4:5]
	s_mov_b64 s[4:5], 0x8000
	v_lshl_add_u64 v[32:33], v[32:33], 0, s[4:5]
	s_cmp_eq_u32 s2, 0
	s_cbranch_scc0 .LBB0_486
	v_add_u32_e32 v74, s85, v74
	s_mov_b32 s2, 0x1ffff
	v_cmp_lt_i32_e32 vcc, s2, v74
	v_readlane_b32 s2, v247, 27
	s_or_b64 s[48:49], vcc, s[48:49]
	s_nop 0
	v_add_u32_e32 v75, s2, v75
	s_andn2_b64 exec, exec, s[48:49]
	s_cbranch_execnz .LBB0_483
